# GEMM main loops (in-proj + out-proj): LDS-DMA loads use SGPR-base + 32-bit VGPR-offset form, 16 v_lshl_add_u64 per iteration removed (on top of v17)
# speedup vs baseline: 1.0031x; 1.0031x over previous
; #define PG8_STAGE(bufoff, gbase, voff) do { _Pragma("unroll") for (int _i = 0; _i < 2; ++_i) \
;         __builtin_amdgcn_global_load_lds((const unsigned*)((const char*)(gbase) + (voff)[_i]), (PG8_LAS unsigned*)(lds + (bufoff) + ldsw + _i * 8192), 16, 0, 0); } while (0)
; #define PG8_LDA(dst, b, h) do { _Pragma("unroll") for (int m = 0; m < 4; ++m) _Pragma("unroll") for (int k = 0; k < 2; ++k) dst[m][k] = *(const PG8_LAS bf16x8*)(lds + PG8_SA(b, h) + aoff + m * 2048 + k * 1024); } while (0)
; #define PG8_LDB(dst, b, h) do { _Pragma("unroll") for (int n = 0; n < 2; ++n) _Pragma("unroll") for (int k = 0; k < 2; ++k) dst[n][k] = *(const PG8_LAS bf16x8*)(lds + PG8_SB(b, h) + boff + n * 2048 + k * 1024); } while (0)
; #define PG8_MMA(ai, bj, At, Bt) do { __builtin_amdgcn_s_setprio(1); _Pragma("unroll") for (int m = 0; m < 4; ++m) _Pragma("unroll") for (int n = 0; n < 2; ++n) _Pragma("unroll") for (int k = 0; k < 2; ++k) \
;         acc[ai][bj][m][n] = __builtin_amdgcn_mfma_f32_16x16x32_bf16(Bt[n][k], At[m][k], acc[ai][bj][m][n], 0, 0, 0); __builtin_amdgcn_s_setprio(0); } while (0)
; #define PG8_WAIT_V(n) asm volatile("s_waitcnt vmcnt(" #n ")" ::: "memory")
; #define PG8_WAIT_L(n) asm volatile("s_waitcnt lgkmcnt(" #n ")" ::: "memory")
; #define PG8_BAR __builtin_amdgcn_s_barrier()
; #define PG8_SCHED __builtin_amdgcn_sched_barrier(0)
; template <class Epi, class Sched, bool ALIGN_EPI = false, bool SP2 = false>
; __device__ __forceinline__ void gemm_phase(PG8_LAS unsigned char* lds, const Gemm g, const Sched& S, const Epi& E, const int tid) {
;     ...
;             if constexpr (SP2) {
;             PG8_LDB(B0, 0, 0); PG8_LDB(B1, 0, 1); PG8_SCHED; PG8_LDA(At, 0, 0); PG8_STAGE(PG8_SA(1, 1), a1 + hstep, voffA);
;             PG8_WAIT_V(8); PG8_WAIT_L(0); PG8_BAR; PG8_MMA(0, 0, At, B0); PG8_MMA(0, 1, At, B1); PG8_BAR; PG8_SCHED;
;             PG8_LDA(At, 0, 1); PG8_STAGE(PG8_SB(0, 0), b2, voffB); PG8_STAGE(PG8_SB(0, 1), b2 + hstep, voffB); PG8_STAGE(PG8_SA(0, 0), a2, voffA);
;             PG8_WAIT_V(8); PG8_WAIT_L(0); PG8_BAR; PG8_MMA(1, 0, At, B0); PG8_MMA(1, 1, At, B1); PG8_BAR; PG8_SCHED;
.LBB0_60:
	s_add_u32 s16, s14, 0xfff80080
	s_addc_u32 s17, s15, -1
	s_add_i32 s43, 0, 0x10000
	s_cmp_eq_u32 s42, 28
	s_cselect_b32 s19, s9, s17
	s_cselect_b32 s18, s38, s16
	v_add_u32_e32 v152, s43, v170
	s_cselect_b32 s17, s7, s41
	s_cselect_b32 s16, s39, s40
	s_add_i32 s46, 0, 0x14000
	ds_read_b128 v[174:177], v152
	ds_read_b128 v[178:181], v152 offset:1024
	ds_read_b128 v[182:185], v152 offset:2048
	ds_read_b128 v[186:189], v152 offset:3072
	v_add_u32_e32 v152, s46, v170
	ds_read_b128 v[190:193], v152
	ds_read_b128 v[194:197], v152 offset:1024
	ds_read_b128 v[198:201], v152 offset:2048
	ds_read_b128 v[202:205], v152 offset:3072
	s_add_i32 m0, s3, 0xc000
	ds_read_b128 v[216:219], v172
	ds_read_b128 v[220:223], v172 offset:1024
	ds_read_b128 v[224:227], v172 offset:2048
	ds_read_b128 v[228:231], v172 offset:3072
	ds_read_b128 v[232:235], v172 offset:4096
	ds_read_b128 v[236:239], v172 offset:5120
	ds_read_b128 v[240:243], v172 offset:6144
	ds_read_b128 v[244:247], v172 offset:7168
	global_load_lds_dwordx4 v136, s[14:15]
	s_add_i32 m0, s3, 0xe000
	s_nop 0
	global_load_lds_dwordx4 v138, s[14:15]
	s_waitcnt vmcnt(8)
	s_waitcnt lgkmcnt(0)
	s_barrier
	s_setprio 1
	s_waitcnt lgkmcnt(0)
	v_mfma_f32_16x16x32_bf16 v[126:129], v[174:177], v[216:219], v[126:129]
	v_mfma_f32_16x16x32_bf16 v[122:125], v[182:185], v[216:219], v[122:125]
	v_mfma_f32_16x16x32_bf16 v[118:121], v[174:177], v[224:227], v[118:121]
	v_mfma_f32_16x16x32_bf16 v[114:117], v[182:185], v[224:227], v[114:117]
	v_mfma_f32_16x16x32_bf16 v[102:105], v[174:177], v[232:235], v[102:105]
	v_mfma_f32_16x16x32_bf16 v[98:101], v[182:185], v[232:235], v[98:101]
	v_mfma_f32_16x16x32_bf16 v[86:89], v[174:177], v[240:243], v[86:89]
	v_mfma_f32_16x16x32_bf16 v[82:85], v[182:185], v[240:243], v[82:85]
	v_mfma_f32_16x16x32_bf16 v[126:129], v[178:181], v[220:223], v[126:129]
	v_mfma_f32_16x16x32_bf16 v[122:125], v[186:189], v[220:223], v[122:125]
	v_mfma_f32_16x16x32_bf16 v[118:121], v[178:181], v[228:231], v[118:121]
	v_mfma_f32_16x16x32_bf16 v[114:117], v[186:189], v[228:231], v[114:117]
	v_mfma_f32_16x16x32_bf16 v[102:105], v[178:181], v[236:239], v[102:105]
	v_mfma_f32_16x16x32_bf16 v[98:101], v[186:189], v[236:239], v[98:101]
	v_mfma_f32_16x16x32_bf16 v[86:89], v[178:181], v[244:247], v[86:89]
	v_mfma_f32_16x16x32_bf16 v[82:85], v[186:189], v[244:247], v[82:85]
	s_setprio 0
	s_setprio 1
	v_mfma_f32_16x16x32_bf16 v[110:113], v[190:193], v[216:219], v[110:113]
	v_mfma_f32_16x16x32_bf16 v[106:109], v[198:201], v[216:219], v[106:109]
	v_mfma_f32_16x16x32_bf16 v[94:97], v[190:193], v[224:227], v[94:97]
	v_mfma_f32_16x16x32_bf16 v[90:93], v[198:201], v[224:227], v[90:93]
	v_mfma_f32_16x16x32_bf16 v[78:81], v[190:193], v[232:235], v[78:81]
	v_mfma_f32_16x16x32_bf16 v[74:77], v[198:201], v[232:235], v[74:77]
	v_mfma_f32_16x16x32_bf16 v[70:73], v[190:193], v[240:243], v[70:73]
	v_mfma_f32_16x16x32_bf16 v[66:69], v[198:201], v[240:243], v[66:69]
	v_mfma_f32_16x16x32_bf16 v[110:113], v[194:197], v[220:223], v[110:113]
	v_mfma_f32_16x16x32_bf16 v[106:109], v[202:205], v[220:223], v[106:109]
	v_mfma_f32_16x16x32_bf16 v[94:97], v[194:197], v[228:231], v[94:97]
	v_mfma_f32_16x16x32_bf16 v[90:93], v[202:205], v[228:231], v[90:93]
	v_mfma_f32_16x16x32_bf16 v[78:81], v[194:197], v[236:239], v[78:81]
	v_mfma_f32_16x16x32_bf16 v[74:77], v[202:205], v[236:239], v[74:77]
	v_mfma_f32_16x16x32_bf16 v[70:73], v[194:197], v[244:247], v[70:73]
	v_mfma_f32_16x16x32_bf16 v[66:69], v[202:205], v[244:247], v[66:69]
	s_setprio 0
	s_barrier
	s_add_i32 s43, s43, s26
	s_mov_b32 m0, s43
	ds_read_b128 v[216:219], v172 offset:16384
	ds_read_b128 v[220:223], v172 offset:17408
	ds_read_b128 v[224:227], v172 offset:18432
	ds_read_b128 v[228:231], v172 offset:19456
	ds_read_b128 v[232:235], v172 offset:20480
	ds_read_b128 v[236:239], v172 offset:21504
	ds_read_b128 v[240:243], v172 offset:22528
	ds_read_b128 v[244:247], v172 offset:23552
	global_load_lds_dwordx4 v0, s[16:17]
	s_add_i32 m0, s43, 0x2000
	s_add_u32 s44, s16, 0x80000
	s_addc_u32 s45, s17, 0
	s_add_i32 s43, s46, s26
	global_load_lds_dwordx4 v134, s[16:17]
	s_mov_b32 m0, s43
	s_nop 0
	global_load_lds_dwordx4 v0, s[44:45]
	s_add_i32 m0, s43, 0x2000
	s_nop 0
	global_load_lds_dwordx4 v134, s[44:45]
	s_mov_b32 m0, s3
	s_nop 0
	global_load_lds_dwordx4 v130, s[18:19]
	s_mov_b32 m0, s27
	s_nop 0
	global_load_lds_dwordx4 v132, s[18:19]
	s_waitcnt vmcnt(8)
	s_waitcnt lgkmcnt(0)
	s_barrier
	s_setprio 1
	s_waitcnt lgkmcnt(0)
	v_mfma_f32_16x16x32_bf16 v[62:65], v[174:177], v[216:219], v[62:65]
	v_mfma_f32_16x16x32_bf16 v[58:61], v[182:185], v[216:219], v[58:61]
	v_mfma_f32_16x16x32_bf16 v[54:57], v[174:177], v[224:227], v[54:57]
	v_mfma_f32_16x16x32_bf16 v[50:53], v[182:185], v[224:227], v[50:53]
	v_mfma_f32_16x16x32_bf16 v[38:41], v[174:177], v[232:235], v[38:41]
	v_mfma_f32_16x16x32_bf16 v[34:37], v[182:185], v[232:235], v[34:37]
	v_mfma_f32_16x16x32_bf16 v[22:25], v[174:177], v[240:243], v[22:25]
	v_mfma_f32_16x16x32_bf16 v[18:21], v[182:185], v[240:243], v[18:21]
	v_mfma_f32_16x16x32_bf16 v[62:65], v[178:181], v[220:223], v[62:65]
	v_mfma_f32_16x16x32_bf16 v[58:61], v[186:189], v[220:223], v[58:61]
	v_mfma_f32_16x16x32_bf16 v[54:57], v[178:181], v[228:231], v[54:57]
	v_mfma_f32_16x16x32_bf16 v[50:53], v[186:189], v[228:231], v[50:53]
	v_mfma_f32_16x16x32_bf16 v[38:41], v[178:181], v[236:239], v[38:41]
	v_mfma_f32_16x16x32_bf16 v[34:37], v[186:189], v[236:239], v[34:37]
	v_mfma_f32_16x16x32_bf16 v[22:25], v[178:181], v[244:247], v[22:25]
	v_mfma_f32_16x16x32_bf16 v[18:21], v[186:189], v[244:247], v[18:21]
	s_setprio 0
	s_setprio 1
	v_mfma_f32_16x16x32_bf16 v[46:49], v[190:193], v[216:219], v[46:49]
	v_mfma_f32_16x16x32_bf16 v[42:45], v[198:201], v[216:219], v[42:45]
	v_mfma_f32_16x16x32_bf16 v[30:33], v[190:193], v[224:227], v[30:33]
	v_mfma_f32_16x16x32_bf16 v[26:29], v[198:201], v[224:227], v[26:29]
	v_mfma_f32_16x16x32_bf16 v[14:17], v[190:193], v[232:235], v[14:17]
	v_mfma_f32_16x16x32_bf16 v[10:13], v[198:201], v[232:235], v[10:13]
	v_mfma_f32_16x16x32_bf16 v[6:9], v[190:193], v[240:243], v[6:9]
	v_mfma_f32_16x16x32_bf16 v[2:5], v[198:201], v[240:243], v[2:5]
	v_mfma_f32_16x16x32_bf16 v[46:49], v[194:197], v[220:223], v[46:49]
	v_mfma_f32_16x16x32_bf16 v[42:45], v[202:205], v[220:223], v[42:45]
	v_mfma_f32_16x16x32_bf16 v[30:33], v[194:197], v[228:231], v[30:33]
	v_mfma_f32_16x16x32_bf16 v[26:29], v[202:205], v[228:231], v[26:29]
	v_mfma_f32_16x16x32_bf16 v[14:17], v[194:197], v[236:239], v[14:17]
	v_mfma_f32_16x16x32_bf16 v[10:13], v[202:205], v[236:239], v[10:13]
	v_mfma_f32_16x16x32_bf16 v[6:9], v[194:197], v[244:247], v[6:9]
	v_mfma_f32_16x16x32_bf16 v[2:5], v[202:205], v[244:247], v[2:5]
	s_setprio 0
	s_barrier
; #define PG8_STAGE(bufoff, gbase, voff) do { _Pragma("unroll") for (int _i = 0; _i < 2; ++_i) \
;         __builtin_amdgcn_global_load_lds((const unsigned*)((const char*)(gbase) + (voff)[_i]), (PG8_LAS unsigned*)(lds + (bufoff) + ldsw + _i * 8192), 16, 0, 0); } while (0)
; #define PG8_LDA(dst, b, h) do { _Pragma("unroll") for (int m = 0; m < 4; ++m) _Pragma("unroll") for (int k = 0; k < 2; ++k) dst[m][k] = *(const PG8_LAS bf16x8*)(lds + PG8_SA(b, h) + aoff + m * 2048 + k * 1024); } while (0)
; #define PG8_LDB(dst, b, h) do { _Pragma("unroll") for (int n = 0; n < 2; ++n) _Pragma("unroll") for (int k = 0; k < 2; ++k) dst[n][k] = *(const PG8_LAS bf16x8*)(lds + PG8_SB(b, h) + boff + n * 2048 + k * 1024); } while (0)
; #define PG8_MMA(ai, bj, At, Bt) do { __builtin_amdgcn_s_setprio(1); _Pragma("unroll") for (int m = 0; m < 4; ++m) _Pragma("unroll") for (int n = 0; n < 2; ++n) _Pragma("unroll") for (int k = 0; k < 2; ++k) \
;         acc[ai][bj][m][n] = __builtin_amdgcn_mfma_f32_16x16x32_bf16(Bt[n][k], At[m][k], acc[ai][bj][m][n], 0, 0, 0); __builtin_amdgcn_s_setprio(0); } while (0)
; #define PG8_WAIT_V(n) asm volatile("s_waitcnt vmcnt(" #n ")" ::: "memory")
; #define PG8_WAIT_L(n) asm volatile("s_waitcnt lgkmcnt(" #n ")" ::: "memory")
; #define PG8_BAR __builtin_amdgcn_s_barrier()
; #define PG8_SCHED __builtin_amdgcn_sched_barrier(0)
; template <class Epi, class Sched, bool ALIGN_EPI = false, bool SP2 = false>
; __device__ __forceinline__ void gemm_phase(PG8_LAS unsigned char* lds, const Gemm g, const Sched& S, const Epi& E, const int tid) {
;     ...
;             PG8_LDB(B0, 1, 0); PG8_LDB(B1, 1, 1); PG8_SCHED; PG8_LDA(At, 1, 0); PG8_STAGE(PG8_SA(0, 1), a2 + hstep, voffA);
;             PG8_WAIT_V(8); PG8_WAIT_L(0); PG8_BAR; PG8_MMA(0, 0, At, B0); PG8_MMA(0, 1, At, B1); PG8_BAR; PG8_SCHED;
;             PG8_LDA(At, 1, 1); PG8_STAGE(PG8_SB(1, 0), b3, voffB); PG8_STAGE(PG8_SB(1, 1), b3 + hstep, voffB); PG8_STAGE(PG8_SA(1, 0), a3, voffA);
;             PG8_WAIT_V(8); PG8_WAIT_L(0); PG8_BAR; PG8_MMA(1, 0, At, B0); PG8_MMA(1, 1, At, B1); PG8_BAR; PG8_SCHED;
	s_add_i32 s43, 0, 0x18000
	v_add_u32_e32 v173, s43, v170
	s_add_i32 s44, 0, 0x1c000
	ds_read_b128 v[174:177], v173
	ds_read_b128 v[178:181], v173 offset:1024
	ds_read_b128 v[182:185], v173 offset:2048
	ds_read_b128 v[186:189], v173 offset:3072
	v_add_u32_e32 v173, s44, v170
	ds_read_b128 v[190:193], v173
	ds_read_b128 v[194:197], v173 offset:1024
	ds_read_b128 v[198:201], v173 offset:2048
	ds_read_b128 v[202:205], v173 offset:3072
	s_add_u32 s18, s18, 0x80000
	s_addc_u32 s19, s19, 0
	s_mov_b32 m0, s28
	ds_read_b128 v[216:219], v172 offset:32768
	ds_read_b128 v[220:223], v172 offset:33792
	ds_read_b128 v[224:227], v172 offset:34816
	ds_read_b128 v[228:231], v172 offset:35840
	ds_read_b128 v[232:235], v172 offset:36864
	ds_read_b128 v[236:239], v172 offset:37888
	ds_read_b128 v[240:243], v172 offset:38912
	ds_read_b128 v[244:247], v172 offset:39936
	global_load_lds_dwordx4 v130, s[18:19]
	s_mov_b32 m0, s30
	s_nop 0
	global_load_lds_dwordx4 v132, s[18:19]
	s_waitcnt vmcnt(8)
	s_waitcnt lgkmcnt(0)
	s_barrier
	s_setprio 1
	s_waitcnt lgkmcnt(0)
	v_mfma_f32_16x16x32_bf16 v[126:129], v[174:177], v[216:219], v[126:129]
	v_mfma_f32_16x16x32_bf16 v[122:125], v[182:185], v[216:219], v[122:125]
	v_mfma_f32_16x16x32_bf16 v[118:121], v[174:177], v[224:227], v[118:121]
	v_mfma_f32_16x16x32_bf16 v[114:117], v[182:185], v[224:227], v[114:117]
	v_mfma_f32_16x16x32_bf16 v[102:105], v[174:177], v[232:235], v[102:105]
	v_mfma_f32_16x16x32_bf16 v[98:101], v[182:185], v[232:235], v[98:101]
	v_mfma_f32_16x16x32_bf16 v[86:89], v[174:177], v[240:243], v[86:89]
	v_mfma_f32_16x16x32_bf16 v[82:85], v[182:185], v[240:243], v[82:85]
	v_mfma_f32_16x16x32_bf16 v[126:129], v[178:181], v[220:223], v[126:129]
	v_mfma_f32_16x16x32_bf16 v[122:125], v[186:189], v[220:223], v[122:125]
	v_mfma_f32_16x16x32_bf16 v[118:121], v[178:181], v[228:231], v[118:121]
	v_mfma_f32_16x16x32_bf16 v[114:117], v[186:189], v[228:231], v[114:117]
	v_mfma_f32_16x16x32_bf16 v[102:105], v[178:181], v[236:239], v[102:105]
	v_mfma_f32_16x16x32_bf16 v[98:101], v[186:189], v[236:239], v[98:101]
	v_mfma_f32_16x16x32_bf16 v[86:89], v[178:181], v[244:247], v[86:89]
	v_mfma_f32_16x16x32_bf16 v[82:85], v[186:189], v[244:247], v[82:85]
	s_setprio 0
	s_setprio 1
	v_mfma_f32_16x16x32_bf16 v[110:113], v[190:193], v[216:219], v[110:113]
	v_mfma_f32_16x16x32_bf16 v[106:109], v[198:201], v[216:219], v[106:109]
	v_mfma_f32_16x16x32_bf16 v[94:97], v[190:193], v[224:227], v[94:97]
	v_mfma_f32_16x16x32_bf16 v[90:93], v[198:201], v[224:227], v[90:93]
	v_mfma_f32_16x16x32_bf16 v[78:81], v[190:193], v[232:235], v[78:81]
	v_mfma_f32_16x16x32_bf16 v[74:77], v[198:201], v[232:235], v[74:77]
	v_mfma_f32_16x16x32_bf16 v[70:73], v[190:193], v[240:243], v[70:73]
	v_mfma_f32_16x16x32_bf16 v[66:69], v[198:201], v[240:243], v[66:69]
	v_mfma_f32_16x16x32_bf16 v[110:113], v[194:197], v[220:223], v[110:113]
	v_mfma_f32_16x16x32_bf16 v[106:109], v[202:205], v[220:223], v[106:109]
	v_mfma_f32_16x16x32_bf16 v[94:97], v[194:197], v[228:231], v[94:97]
	v_mfma_f32_16x16x32_bf16 v[90:93], v[202:205], v[228:231], v[90:93]
	v_mfma_f32_16x16x32_bf16 v[78:81], v[194:197], v[236:239], v[78:81]
	v_mfma_f32_16x16x32_bf16 v[74:77], v[202:205], v[236:239], v[74:77]
	v_mfma_f32_16x16x32_bf16 v[70:73], v[194:197], v[244:247], v[70:73]
	v_mfma_f32_16x16x32_bf16 v[66:69], v[202:205], v[244:247], v[66:69]
	s_setprio 0
	s_barrier
	s_add_i32 m0, s43, s26
	s_add_u32 s16, s16, 0x80
	s_addc_u32 s17, s17, 0
	ds_read_b128 v[216:219], v172 offset:49152
	ds_read_b128 v[220:223], v172 offset:50176
	ds_read_b128 v[224:227], v172 offset:51200
	ds_read_b128 v[228:231], v172 offset:52224
	ds_read_b128 v[232:235], v172 offset:53248
	ds_read_b128 v[236:239], v172 offset:54272
	ds_read_b128 v[240:243], v172 offset:55296
	ds_read_b128 v[244:247], v172 offset:56320
	global_load_lds_dwordx4 v0, s[16:17]
	s_add_i32 m0, m0, 0x2000
	s_nop 0
	global_load_lds_dwordx4 v134, s[16:17]
	s_add_u32 s16, s16, 0x80000
	s_addc_u32 s17, s17, 0
	s_add_i32 m0, s44, s26
	s_nop 0
	global_load_lds_dwordx4 v0, s[16:17]
	s_add_i32 m0, m0, 0x2000
	s_nop 0
	global_load_lds_dwordx4 v134, s[16:17]
	s_add_u32 s18, s18, 0xfff80080
	s_addc_u32 s19, s19, -1
	s_mov_b32 m0, s31
	s_nop 0
	global_load_lds_dwordx4 v130, s[18:19]
	s_mov_b32 m0, s34
	s_nop 0
	global_load_lds_dwordx4 v132, s[18:19]
	s_waitcnt vmcnt(8)
	s_waitcnt lgkmcnt(0)
	s_barrier
	s_setprio 1
	s_waitcnt lgkmcnt(0)
	v_mfma_f32_16x16x32_bf16 v[62:65], v[174:177], v[216:219], v[62:65]
	v_mfma_f32_16x16x32_bf16 v[58:61], v[182:185], v[216:219], v[58:61]
	v_mfma_f32_16x16x32_bf16 v[54:57], v[174:177], v[224:227], v[54:57]
	v_mfma_f32_16x16x32_bf16 v[50:53], v[182:185], v[224:227], v[50:53]
	v_mfma_f32_16x16x32_bf16 v[38:41], v[174:177], v[232:235], v[38:41]
	v_mfma_f32_16x16x32_bf16 v[34:37], v[182:185], v[232:235], v[34:37]
	v_mfma_f32_16x16x32_bf16 v[22:25], v[174:177], v[240:243], v[22:25]
	v_mfma_f32_16x16x32_bf16 v[18:21], v[182:185], v[240:243], v[18:21]
	v_mfma_f32_16x16x32_bf16 v[62:65], v[178:181], v[220:223], v[62:65]
	v_mfma_f32_16x16x32_bf16 v[58:61], v[186:189], v[220:223], v[58:61]
	v_mfma_f32_16x16x32_bf16 v[54:57], v[178:181], v[228:231], v[54:57]
	v_mfma_f32_16x16x32_bf16 v[50:53], v[186:189], v[228:231], v[50:53]
	v_mfma_f32_16x16x32_bf16 v[38:41], v[178:181], v[236:239], v[38:41]
	v_mfma_f32_16x16x32_bf16 v[34:37], v[186:189], v[236:239], v[34:37]
	v_mfma_f32_16x16x32_bf16 v[22:25], v[178:181], v[244:247], v[22:25]
	v_mfma_f32_16x16x32_bf16 v[18:21], v[186:189], v[244:247], v[18:21]
	s_setprio 0
	s_setprio 1
	v_mfma_f32_16x16x32_bf16 v[46:49], v[190:193], v[216:219], v[46:49]
	v_mfma_f32_16x16x32_bf16 v[42:45], v[198:201], v[216:219], v[42:45]
	v_mfma_f32_16x16x32_bf16 v[30:33], v[190:193], v[224:227], v[30:33]
	v_mfma_f32_16x16x32_bf16 v[26:29], v[198:201], v[224:227], v[26:29]
	v_mfma_f32_16x16x32_bf16 v[14:17], v[190:193], v[232:235], v[14:17]
	v_mfma_f32_16x16x32_bf16 v[10:13], v[198:201], v[232:235], v[10:13]
	v_mfma_f32_16x16x32_bf16 v[6:9], v[190:193], v[240:243], v[6:9]
	v_mfma_f32_16x16x32_bf16 v[2:5], v[198:201], v[240:243], v[2:5]
	v_mfma_f32_16x16x32_bf16 v[46:49], v[194:197], v[220:223], v[46:49]
	v_mfma_f32_16x16x32_bf16 v[42:45], v[202:205], v[220:223], v[42:45]
	v_mfma_f32_16x16x32_bf16 v[30:33], v[194:197], v[228:231], v[30:33]
	v_mfma_f32_16x16x32_bf16 v[26:29], v[202:205], v[228:231], v[26:29]
	v_mfma_f32_16x16x32_bf16 v[14:17], v[194:197], v[236:239], v[14:17]
	v_mfma_f32_16x16x32_bf16 v[10:13], v[202:205], v[236:239], v[10:13]
	v_mfma_f32_16x16x32_bf16 v[6:9], v[194:197], v[244:247], v[6:9]
	v_mfma_f32_16x16x32_bf16 v[2:5], v[202:205], v[244:247], v[2:5]
	s_setprio 0
	s_barrier
; #define PG8_WAIT_V(n) asm volatile("s_waitcnt vmcnt(" #n ")" ::: "memory")
; #define PG8_BAR __builtin_amdgcn_s_barrier()
; __device__ __forceinline__ unsigned pk2(float lo, float hi) { f32x2 v = {lo, hi}; hbf2 b = __builtin_convertvector(v, hbf2); return __builtin_bit_cast(unsigned, b); }
; template <class Epi, class Sched, bool ALIGN_EPI = false, bool SP2 = false>
; __device__ __forceinline__ void gemm_phase(PG8_LAS unsigned char* lds, const Gemm g, const Sched& S, const Epi& E, const int tid) {
;     ...
;         }
;         if constexpr (ALIGN_EPI) { if (wr == 0) PG8_BAR; }
;         if constexpr (!Epi::AFTER_DRAIN) { E(acc, cur, wr, wc, fr, fq); S.done(cur); }
;         if (!has_next) break;
; #pragma unroll
;         for (int a = 0; a < 2; ++a)
; #pragma unroll
;             for (int b = 0; b < 2; ++b)
; #pragma unroll
;                 for (int m = 0; m < 4; ++m)
; #pragma unroll
;                     for (int n = 0; n < 2; ++n) acc[a][b][m][n] = (f32x4){0.f, 0.f, 0.f, 0.f};
;         cur = nxt; cA = nA; cB = nB; ++ui;
;         if constexpr (ALIGN_EPI) { if (wr == 1) PG8_BAR; }
;     }
;     PG8_WAIT_V(0);
;     if constexpr (!ALIGN_EPI) { if (wr == 0) PG8_BAR; }
;     PG8_BAR;
;     __device__ __forceinline__ void operator()(const f32x4 (&acc)[2][2][4][2], const Unit& u, int wr, int wc, int fr, int fq) const {
;         const int row0 = u.pm * BM + wr * 64 + fr, col0 = u.pn * BM + wc * 32 + 8 * fq;
; #pragma unroll
;         for (int ai = 0; ai < 2; ++ai)
; #pragma unroll
;             for (int m = 0; m < 4; ++m) { bf16_t* rowp = O + (size_t)(row0 + ai * HALF + m * 16) * ldc + col0;
; #pragma unroll
;                 for (int bj = 0; bj < 2; ++bj) { const f32x4 v0 = acc[ai][bj][m][0], v1 = acc[ai][bj][m][1];
;                     u32x4 w; w.x = pk2(v0[0], v0[1]); w.y = pk2(v0[2], v0[3]); w.z = pk2(v1[0], v1[1]); w.w = pk2(v1[2], v1[3]);
;                     if constexpr (NT) __builtin_nontemporal_store(w, (u32x4*)(rowp + bj * HALF)); else *(u32x4*)(rowp + bj * HALF) = w; } }
	s_add_i32 s42, s42, 2
	s_add_u32 s14, s14, 0x100
	s_addc_u32 s15, s15, 0
	s_add_u32 s40, s40, 0x100
	s_addc_u32 s41, s41, 0
	s_cmp_gt_u32 s42, 29
	s_cbranch_scc0 .LBB0_60
	v_lshl_add_u32 v174, s2, 8, v169
	v_lshl_or_b32 v176, s37, 8, v171
	v_ashrrev_i32_e32 v175, 31, v174
	v_ashrrev_i32_e32 v177, 31, v176
	v_lshlrev_b64 v[178:179], 14, v[174:175]
	v_lshl_add_u64 v[178:179], s[84:85], 0, v[178:179]
	v_lshlrev_b64 v[176:177], 1, v[176:177]
	v_lshl_add_u64 v[178:179], v[178:179], 0, v[176:177]
	s_mov_b32 s2, 0x200000
	s_mov_b64 s[14:15], 0x200000
	v_cvt_pk_bf16_f32 v62, v62, v63
	v_cvt_pk_bf16_f32 v63, v64, v65
	v_cvt_pk_bf16_f32 v64, v58, v59
	v_add_co_u32_e32 v58, vcc, s2, v178
	v_cvt_pk_bf16_f32 v70, v70, v71
	v_cvt_pk_bf16_f32 v71, v72, v73
	v_cvt_pk_bf16_f32 v72, v66, v67
	v_lshl_add_u64 v[66:67], v[178:179], 0, s[14:15]
	v_addc_co_u32_e32 v59, vcc, 0, v179, vcc
	v_cvt_pk_bf16_f32 v46, v46, v47
	v_cvt_pk_bf16_f32 v47, v48, v49
	v_cvt_pk_bf16_f32 v48, v42, v43
	v_cvt_pk_bf16_f32 v49, v44, v45
	s_mov_b32 s2, 0x240000
	v_cvt_pk_bf16_f32 v110, v110, v111
	v_cvt_pk_bf16_f32 v111, v112, v113
	v_cvt_pk_bf16_f32 v112, v106, v107
	v_or_b32_e32 v106, 16, v174
	global_store_dwordx4 v[66:67], v[46:49], off offset:256 nt
	s_mov_b64 s[14:15], 0x240000
	v_ashrrev_i32_e32 v107, 31, v106
	v_add_co_u32_e32 v48, vcc, s2, v178
	v_cvt_pk_bf16_f32 v94, v94, v95
	v_cvt_pk_bf16_f32 v95, v96, v97
	v_cvt_pk_bf16_f32 v96, v90, v91
	v_or_b32_e32 v90, 32, v174
	v_lshl_add_u64 v[46:47], v[178:179], 0, s[14:15]
	v_addc_co_u32_e32 v49, vcc, 0, v179, vcc
	v_cvt_pk_bf16_f32 v30, v30, v31
	v_cvt_pk_bf16_f32 v31, v32, v33
	v_cvt_pk_bf16_f32 v32, v26, v27
	v_cvt_pk_bf16_f32 v33, v28, v29
	s_mov_b32 s2, 0x280000
	v_lshlrev_b64 v[106:107], 14, v[106:107]
	v_ashrrev_i32_e32 v91, 31, v90
	v_cvt_pk_bf16_f32 v78, v78, v79
	v_cvt_pk_bf16_f32 v79, v80, v81
	v_cvt_pk_bf16_f32 v80, v74, v75
	v_or_b32_e32 v74, 48, v174
	global_store_dwordx4 v[46:47], v[30:33], off offset:256 nt
	s_mov_b64 s[14:15], 0x280000
	v_cvt_pk_bf16_f32 v113, v108, v109
	v_add_co_u32_e32 v32, vcc, s2, v178
	v_lshl_add_u64 v[106:107], s[84:85], 0, v[106:107]
	v_lshlrev_b64 v[90:91], 14, v[90:91]
	v_ashrrev_i32_e32 v75, 31, v74
	v_lshl_add_u64 v[30:31], v[178:179], 0, s[14:15]
	v_addc_co_u32_e32 v33, vcc, 0, v179, vcc
	v_cvt_pk_bf16_f32 v14, v14, v15
	v_cvt_pk_bf16_f32 v15, v16, v17
	v_cvt_pk_bf16_f32 v16, v10, v11
	v_cvt_pk_bf16_f32 v17, v12, v13
	s_mov_b32 s2, 0x2c0000
	global_store_dwordx4 v[178:179], v[110:113], off offset:256 nt
	v_cvt_pk_bf16_f32 v97, v92, v93
	v_lshl_add_u64 v[90:91], s[84:85], 0, v[90:91]
	v_lshl_add_u64 v[110:111], v[106:107], 0, v[176:177]
	v_lshlrev_b64 v[74:75], 14, v[74:75]
	global_store_dwordx4 v[30:31], v[14:17], off offset:256 nt
	global_store_dwordx4 v[110:111], v[94:97], off offset:256 nt
	v_cvt_pk_bf16_f32 v81, v76, v77
	v_add_co_u32_e32 v16, vcc, s2, v178
	v_lshl_add_u64 v[94:95], v[90:91], 0, v[176:177]
	v_lshl_add_u64 v[74:75], s[84:85], 0, v[74:75]
	s_mov_b64 s[14:15], 0x2c0000
	v_addc_co_u32_e32 v17, vcc, 0, v179, vcc
	v_cvt_pk_bf16_f32 v126, v126, v127
	v_cvt_pk_bf16_f32 v127, v128, v129
	v_cvt_pk_bf16_f32 v128, v122, v123
	v_cvt_pk_bf16_f32 v129, v124, v125
	v_cvt_pk_bf16_f32 v106, v118, v119
	v_cvt_pk_bf16_f32 v107, v120, v121
	v_cvt_pk_bf16_f32 v108, v114, v115
	v_cvt_pk_bf16_f32 v109, v116, v117
	v_cvt_pk_bf16_f32 v90, v102, v103
	v_cvt_pk_bf16_f32 v91, v104, v105
	v_cvt_pk_bf16_f32 v92, v98, v99
	v_cvt_pk_bf16_f32 v93, v100, v101
	global_store_dwordx4 v[94:95], v[78:81], off offset:256 nt
	v_cvt_pk_bf16_f32 v76, v82, v83
	v_cvt_pk_bf16_f32 v77, v84, v85
	v_lshl_add_u64 v[78:79], v[74:75], 0, v[176:177]
	v_cvt_pk_bf16_f32 v74, v86, v87
	v_cvt_pk_bf16_f32 v75, v88, v89
	v_cvt_pk_bf16_f32 v73, v68, v69
	v_cvt_pk_bf16_f32 v65, v60, v61
	v_cvt_pk_bf16_f32 v42, v54, v55
	v_cvt_pk_bf16_f32 v43, v56, v57
	v_cvt_pk_bf16_f32 v44, v50, v51
	v_cvt_pk_bf16_f32 v45, v52, v53
	v_cvt_pk_bf16_f32 v26, v38, v39
	v_cvt_pk_bf16_f32 v27, v40, v41
	v_cvt_pk_bf16_f32 v28, v34, v35
	v_cvt_pk_bf16_f32 v29, v36, v37
	v_lshl_add_u64 v[14:15], v[178:179], 0, s[14:15]
	v_cvt_pk_bf16_f32 v10, v22, v23
	v_cvt_pk_bf16_f32 v11, v24, v25
	v_cvt_pk_bf16_f32 v12, v18, v19
	v_cvt_pk_bf16_f32 v13, v20, v21
	v_cvt_pk_bf16_f32 v6, v6, v7
	v_cvt_pk_bf16_f32 v7, v8, v9
	v_cvt_pk_bf16_f32 v8, v2, v3
	v_cvt_pk_bf16_f32 v9, v4, v5
	s_and_b64 vcc, exec, s[4:5]
	s_mov_b32 s37, s6
	s_mov_b32 s2, s8
	s_mov_b64 s[16:17], s[12:13]
	s_mov_b64 s[14:15], s[10:11]
	global_store_dwordx4 v[178:179], v[126:129], off nt
	global_store_dwordx4 v[110:111], v[106:109], off nt
	global_store_dwordx4 v[94:95], v[90:93], off nt
	global_store_dwordx4 v[78:79], v[74:77], off nt
	global_store_dwordx4 v[78:79], v[70:73], off offset:256 nt
	global_store_dwordx4 v[58:59], v[62:65], off nt
	global_store_dwordx4 v[48:49], v[42:45], off nt
	global_store_dwordx4 v[32:33], v[26:29], off nt
	global_store_dwordx4 v[16:17], v[10:13], off nt
	global_store_dwordx4 v[14:15], v[6:9], off offset:256 nt
	s_cbranch_vccz .LBB0_53
	s_waitcnt vmcnt(0)
	s_cmpk_gt_u32 s24, 0xff
	s_cbranch_scc1 .LBB0_64
	s_barrier

; __device__ __forceinline__ bf16x8 pack8(f32x4 a, f32x4 b) { u32x4 w = {pk2(a[0], a[1]), pk2(a[2], a[3]), pk2(b[0], b[1]), pk2(b[2], b[3])}; return __builtin_bit_cast(bf16x8, w); }
; #define ATT_VLOAD(g4) do { _Pragma("unroll") for (int d = 0; d < 2; ++d) _Pragma("unroll") for (int k2 = 0; k2 < 2; ++k2) { const bf16_t* vp = vt + (((g4) * 2 + d) * 16 + fr) * 72 + k2 * 32 + fq * 4; \
;                     vf[g4][d][k2] = cat8(*(const bf16x4*)vp, *(const bf16x4*)(vp + 16)); } } while (0)
; #define ATT_VMMA(g4) do { _Pragma("unroll") for (int k2 = 0; k2 < 2; ++k2) _Pragma("unroll") for (int d = 0; d < 2; ++d) _Pragma("unroll") for (int qt = 0; qt < 2; ++qt) \
;                     o[qt][(g4) * 2 + d] = MFMA16(vf[g4][d][k2], pb[qt][k2], o[qt][(g4) * 2 + d]); } while (0)
; __device__ __forceinline__ void attn_phase(unsigned char* lds, const Params& p, int jl, const bf16_t* proj, bf16_t* mix, int blk, int G, int tid) {
;     ...
;                     for (int kt = 0; kt < 4; ++kt) { s[qt][kt] = s[qt][kt] - m_new;
; #pragma unroll
;                         for (int j = 0; j < 4; ++j) s[qt][kt][j] = __builtin_amdgcn_exp2f(s[qt][kt][j]); }
;                     const f32x4 sv4 = (s[qt][0] + s[qt][1]) + (s[qt][2] + s[qt][3]);
;                     const float ps = (sv4[0] + sv4[1]) + (sv4[2] + sv4[3]);
;                     l_run[qt] = l_run[qt] * alpha + ps; m_run[qt] = m_new;
;                     if (__any(alpha != 1.f)) {
; #pragma unroll
;                         for (int dt = 0; dt < 8; ++dt) o[qt][dt] = o[qt][dt] * alpha; }
;                     pb[qt][0] = pack8(s[qt][0], s[qt][1]); pb[qt][1] = pack8(s[qt][2], s[qt][3]);
;                 }
;                 __builtin_amdgcn_sched_barrier(0);
;                 ATT_VLOAD(1); ATT_VMMA(0);
;                 __builtin_amdgcn_sched_barrier(0);
;                 ATT_VLOAD(2); ATT_VMMA(1);
;                 __builtin_amdgcn_sched_barrier(0);
;                 ATT_VLOAD(3); ATT_VMMA(2);
;                 __builtin_amdgcn_sched_barrier(0);
;                 ATT_VMMA(3);
.LBB0_210:
	v_sub_f32_e32 v133, v168, v207
	v_exp_f32_e32 v152, v133
	v_sub_f32_e32 v133, v172, v207
	v_sub_f32_e32 v134, v171, v207
	v_sub_f32_e32 v132, v169, v207
	v_sub_f32_e32 v135, v170, v207
	v_exp_f32_e32 v169, v134
	v_exp_f32_e32 v170, v133
	v_sub_f32_e32 v133, v222, v207
	v_sub_f32_e32 v134, v223, v207
	v_sub_f32_e32 v189, v189, v141
	v_sub_f32_e32 v188, v188, v141
	v_sub_f32_e32 v187, v187, v141
	v_sub_f32_e32 v186, v186, v141
	v_sub_f32_e32 v177, v177, v141
	v_sub_f32_e32 v176, v176, v141
	v_sub_f32_e32 v175, v175, v141
	v_sub_f32_e32 v174, v174, v141
	v_sub_f32_e32 v206, v146, v141
	v_sub_f32_e32 v210, v147, v141
	v_sub_f32_e32 v147, v178, v141
	v_sub_f32_e32 v146, v179, v141
	v_sub_f32_e32 v142, v142, v141
	v_sub_f32_e32 v143, v143, v141
	v_sub_f32_e32 v144, v144, v141
	v_sub_f32_e32 v145, v145, v141
	v_exp_f32_e32 v153, v132
	v_sub_f32_e32 v132, v173, v207
	v_exp_f32_e32 v173, v134
	v_exp_f32_e32 v180, v133
	v_sub_f32_e32 v133, v216, v207
	v_sub_f32_e32 v134, v217, v207
	v_exp_f32_e32 v186, v186
	v_exp_f32_e32 v187, v187
	v_exp_f32_e32 v188, v188
	v_exp_f32_e32 v189, v189
	v_exp_f32_e32 v174, v174
	v_exp_f32_e32 v175, v175
	v_exp_f32_e32 v176, v176
	v_exp_f32_e32 v177, v177
	v_exp_f32_e32 v146, v146
	v_exp_f32_e32 v147, v147
	v_exp_f32_e32 v178, v210
	v_exp_f32_e32 v179, v206
	v_exp_f32_e32 v210, v145
	v_exp_f32_e32 v211, v144
	v_exp_f32_e32 v216, v143
	v_exp_f32_e32 v217, v142
	v_exp_f32_e32 v168, v135
	v_exp_f32_e32 v171, v132
	v_sub_f32_e32 v132, v221, v207
	v_sub_f32_e32 v135, v224, v207
	v_sub_f32_e32 v3, v3, v207
	v_sub_f32_e32 v2, v2, v207
	v_exp_f32_e32 v172, v135
	v_exp_f32_e32 v181, v132
	v_sub_f32_e32 v132, v215, v207
	v_sub_f32_e32 v135, v218, v207
	v_exp_f32_e32 v2, v2
	v_exp_f32_e32 v3, v3
	v_exp_f32_e32 v182, v135
	v_exp_f32_e32 v183, v134
	v_exp_f32_e32 v184, v133
	v_exp_f32_e32 v185, v132
	v_pk_add_f32 v[142:143], v[186:187], v[174:175]
	v_pk_add_f32 v[144:145], v[188:189], v[176:177]
	v_pk_add_f32 v[218:219], v[146:147], v[210:211]
	v_pk_add_f32 v[220:221], v[178:179], v[216:217]
	v_pk_add_f32 v[142:143], v[142:143], v[218:219]
	v_pk_add_f32 v[144:145], v[144:145], v[220:221]
	v_add_f32_e32 v142, v142, v143
	v_add_f32_e32 v143, v144, v145
	v_cvt_pk_bf16_f32 v132, v2, v3
	v_cvt_pk_bf16_f32 v133, v152, v153
	v_add_f32_e32 v215, v142, v143
	v_pk_add_f32 v[2:3], v[2:3], v[168:169]
	v_pk_add_f32 v[142:143], v[152:153], v[170:171]
	v_pk_add_f32 v[144:145], v[172:173], v[182:183]
	v_pk_add_f32 v[152:153], v[180:181], v[184:185]
	v_pk_add_f32 v[2:3], v[2:3], v[144:145]
	v_pk_add_f32 v[142:143], v[142:143], v[152:153]
	v_add_f32_e32 v2, v2, v3
	v_add_f32_e32 v3, v142, v143
	v_fmac_f32_e32 v215, v201, v140
	v_add_f32_e32 v140, v2, v3
	v_cvt_pk_bf16_f32 v134, v168, v169
	v_cvt_pk_bf16_f32 v135, v170, v171
	v_cvt_pk_bf16_f32 v136, v172, v173
	v_cvt_pk_bf16_f32 v137, v180, v181
	v_cvt_pk_bf16_f32 v138, v182, v183
	v_cvt_pk_bf16_f32 v139, v184, v185
	v_fmac_f32_e32 v140, v205, v0
	v_cvt_pk_bf16_f32 v142, v186, v187
	v_cvt_pk_bf16_f32 v143, v188, v189
	v_cvt_pk_bf16_f32 v144, v174, v175
	v_cvt_pk_bf16_f32 v145, v176, v177
	v_cvt_pk_bf16_f32 v168, v146, v147
	v_cvt_pk_bf16_f32 v169, v178, v179
	v_cvt_pk_bf16_f32 v170, v210, v211
	v_cvt_pk_bf16_f32 v171, v216, v217
	v_mfma_f32_16x16x32_bf16 v[104:107], v[124:127], v[132:135], v[104:107]
	v_add3_u32 v0, s21, v161, v160
	v_add_u32_e32 v2, 0x9800, v0
	v_mfma_f32_16x16x32_bf16 v[32:35], v[124:127], v[142:145], v[32:35]
	v_mfma_f32_16x16x32_bf16 v[96:99], v[128:131], v[132:135], v[96:99]
	v_mfma_f32_16x16x32_bf16 v[28:31], v[128:131], v[142:145], v[28:31]
	v_mfma_f32_16x16x32_bf16 v[104:107], v[120:123], v[136:139], v[104:107]
	v_mfma_f32_16x16x32_bf16 v[32:35], v[120:123], v[168:171], v[32:35]
	ds_read_b64 v[120:121], v2 offset:512
	ds_read_b64 v[122:123], v2 offset:544
	ds_read_b64 v[124:125], v2 offset:576
	ds_read_b64 v[126:127], v2 offset:608
	v_add_u32_e32 v2, 0xa000, v0
	ds_read_b64 v[128:129], v2 offset:768
	ds_read_b64 v[130:131], v2 offset:800
	ds_read_b64 v[172:173], v2 offset:832
	ds_read_b64 v[174:175], v2 offset:864
	v_mfma_f32_16x16x32_bf16 v[96:99], v[116:119], v[136:139], v[96:99]
	v_mfma_f32_16x16x32_bf16 v[28:31], v[116:119], v[168:171], v[28:31]
	s_waitcnt lgkmcnt(3)
	v_mfma_f32_16x16x32_bf16 v[88:91], v[120:123], v[132:135], v[88:91]
	v_add_u32_e32 v2, 0xa800, v0
	v_mfma_f32_16x16x32_bf16 v[24:27], v[120:123], v[142:145], v[24:27]
	ds_read_b64 v[116:117], v2 offset:1024
	ds_read_b64 v[118:119], v2 offset:1056
	ds_read_b64 v[120:121], v2 offset:1088
	ds_read_b64 v[122:123], v2 offset:1120
	v_add_u32_e32 v2, 0xb000, v0
	s_waitcnt lgkmcnt(6)
	v_mfma_f32_16x16x32_bf16 v[84:87], v[128:131], v[132:135], v[84:87]
	v_mfma_f32_16x16x32_bf16 v[20:23], v[128:131], v[142:145], v[20:23]
	v_mfma_f32_16x16x32_bf16 v[88:91], v[124:127], v[136:139], v[88:91]
	v_mfma_f32_16x16x32_bf16 v[24:27], v[124:127], v[168:171], v[24:27]
	ds_read_b64 v[124:125], v2 offset:1280
	ds_read_b64 v[126:127], v2 offset:1312
	ds_read_b64 v[128:129], v2 offset:1344
	ds_read_b64 v[130:131], v2 offset:1376
	s_waitcnt lgkmcnt(8)
	v_mfma_f32_16x16x32_bf16 v[84:87], v[172:175], v[136:139], v[84:87]
	v_mfma_f32_16x16x32_bf16 v[20:23], v[172:175], v[168:171], v[20:23]
	s_waitcnt lgkmcnt(6)
	v_mfma_f32_16x16x32_bf16 v[48:51], v[116:119], v[132:135], v[48:51]
	v_add_u32_e32 v2, 0xb800, v0
	v_add_u32_e32 v0, 0xc000, v0
	v_mfma_f32_16x16x32_bf16 v[16:19], v[116:119], v[142:145], v[16:19]
	s_waitcnt lgkmcnt(2)
	v_mfma_f32_16x16x32_bf16 v[44:47], v[124:127], v[132:135], v[44:47]
	v_mfma_f32_16x16x32_bf16 v[12:15], v[124:127], v[142:145], v[12:15]
	v_mfma_f32_16x16x32_bf16 v[48:51], v[120:123], v[136:139], v[48:51]
	v_mfma_f32_16x16x32_bf16 v[16:19], v[120:123], v[168:171], v[16:19]
	ds_read_b64 v[116:117], v2 offset:1536
	ds_read_b64 v[118:119], v2 offset:1568
	ds_read_b64 v[120:121], v2 offset:1600
	ds_read_b64 v[122:123], v2 offset:1632
	ds_read_b64 v[124:125], v0 offset:1792
	ds_read_b64 v[126:127], v0 offset:1824
	ds_read_b64 v[172:173], v0 offset:1856
	ds_read_b64 v[174:175], v0 offset:1888
	s_waitcnt lgkmcnt(8)
	v_mfma_f32_16x16x32_bf16 v[44:47], v[128:131], v[136:139], v[44:47]
	v_mfma_f32_16x16x32_bf16 v[12:15], v[128:131], v[168:171], v[12:15]
	s_waitcnt lgkmcnt(6)
	v_mfma_f32_16x16x32_bf16 v[40:43], v[116:119], v[132:135], v[40:43]
	v_mov_b32_e32 v206, v141
	v_mov_b32_e32 v186, v207
	v_mov_b32_e32 v201, v215
	v_mfma_f32_16x16x32_bf16 v[8:11], v[116:119], v[142:145], v[8:11]
	v_mov_b32_e32 v205, v140
	s_waitcnt lgkmcnt(2)
	v_mfma_f32_16x16x32_bf16 v[36:39], v[124:127], v[132:135], v[36:39]
	v_mfma_f32_16x16x32_bf16 v[2:5], v[124:127], v[142:145], v[4:7]
	v_mfma_f32_16x16x32_bf16 v[40:43], v[120:123], v[136:139], v[40:43]
	v_mfma_f32_16x16x32_bf16 v[8:11], v[120:123], v[168:171], v[8:11]
	s_waitcnt lgkmcnt(0)
	v_mfma_f32_16x16x32_bf16 v[36:39], v[172:175], v[136:139], v[36:39]
	v_mfma_f32_16x16x32_bf16 v[4:7], v[172:175], v[168:171], v[2:5]

; #define PG8_STAGE(bufoff, gbase, voff) do { _Pragma("unroll") for (int _i = 0; _i < 2; ++_i) \
;         __builtin_amdgcn_global_load_lds((const unsigned*)((const char*)(gbase) + (voff)[_i]), (PG8_LAS unsigned*)(lds + (bufoff) + ldsw + _i * 8192), 16, 0, 0); } while (0)
; #define PG8_LDA(dst, b, h) do { _Pragma("unroll") for (int m = 0; m < 4; ++m) _Pragma("unroll") for (int k = 0; k < 2; ++k) dst[m][k] = *(const PG8_LAS bf16x8*)(lds + PG8_SA(b, h) + aoff + m * 2048 + k * 1024); } while (0)
; #define PG8_LDB(dst, b, h) do { _Pragma("unroll") for (int n = 0; n < 2; ++n) _Pragma("unroll") for (int k = 0; k < 2; ++k) dst[n][k] = *(const PG8_LAS bf16x8*)(lds + PG8_SB(b, h) + boff + n * 2048 + k * 1024); } while (0)
; #define PG8_MMA(ai, bj, At, Bt) do { __builtin_amdgcn_s_setprio(1); _Pragma("unroll") for (int m = 0; m < 4; ++m) _Pragma("unroll") for (int n = 0; n < 2; ++n) _Pragma("unroll") for (int k = 0; k < 2; ++k) \
;         acc[ai][bj][m][n] = __builtin_amdgcn_mfma_f32_16x16x32_bf16(Bt[n][k], At[m][k], acc[ai][bj][m][n], 0, 0, 0); __builtin_amdgcn_s_setprio(0); } while (0)
; #define PG8_WAIT_V(n) asm volatile("s_waitcnt vmcnt(" #n ")" ::: "memory")
; #define PG8_WAIT_L(n) asm volatile("s_waitcnt lgkmcnt(" #n ")" ::: "memory")
; template <class Epi, class Sched, bool ALIGN_EPI = false, bool SP2 = false>
; __device__ __forceinline__ void gemm_phase(PG8_LAS unsigned char* lds, const Gemm g, const Sched& S, const Epi& E, const int tid) {
;     ...
;             const bool last = (t == nt - 2);
;             const char* a1 = cA + (size_t)(t + 1) * kstep;
;             const char* a2 = last ? nA : cA + (size_t)(t + 2) * kstep; const char* b2 = last ? nB : cB + (size_t)(t + 2) * kstep;
;             const char* a3 = a2 + kstep; const char* b3 = b2 + kstep;
;             if (last && has_next) S.a_ready(nxt);
;             if constexpr (SP2) {
;             PG8_LDB(B0, 0, 0); PG8_LDB(B1, 0, 1); PG8_SCHED; PG8_LDA(At, 0, 0); PG8_STAGE(PG8_SA(1, 1), a1 + hstep, voffA);
;             PG8_WAIT_V(8); PG8_WAIT_L(0); PG8_BAR; PG8_MMA(0, 0, At, B0); PG8_MMA(0, 1, At, B1); PG8_BAR; PG8_SCHED;
;             PG8_LDA(At, 0, 1); PG8_STAGE(PG8_SB(0, 0), b2, voffB); PG8_STAGE(PG8_SB(0, 1), b2 + hstep, voffB); PG8_STAGE(PG8_SA(0, 0), a2, voffA);
;             PG8_WAIT_V(8); PG8_WAIT_L(0); PG8_BAR; PG8_MMA(1, 0, At, B0); PG8_MMA(1, 1, At, B1); PG8_BAR; PG8_SCHED;
.LBB0_496:
	s_add_u32 s16, s14, 0xfff80080
	s_addc_u32 s17, s15, -1
	s_add_i32 s43, 0, 0x10000
	s_cmp_eq_u32 s42, 28
	s_cselect_b32 s19, s9, s17
	s_cselect_b32 s18, s38, s16
	v_add_u32_e32 v152, s43, v170
	s_cselect_b32 s17, s7, s41
	s_cselect_b32 s16, s39, s40
	s_add_i32 s46, 0, 0x14000
	ds_read_b128 v[174:177], v152
	ds_read_b128 v[178:181], v152 offset:1024
	ds_read_b128 v[182:185], v152 offset:2048
	ds_read_b128 v[186:189], v152 offset:3072
	v_add_u32_e32 v152, s46, v170
	ds_read_b128 v[190:193], v152
	ds_read_b128 v[194:197], v152 offset:1024
	ds_read_b128 v[198:201], v152 offset:2048
	ds_read_b128 v[202:205], v152 offset:3072
	s_add_i32 m0, s3, 0xc000
	ds_read_b128 v[216:219], v172
	ds_read_b128 v[220:223], v172 offset:1024
	ds_read_b128 v[224:227], v172 offset:2048
	ds_read_b128 v[228:231], v172 offset:3072
	ds_read_b128 v[232:235], v172 offset:4096
	ds_read_b128 v[236:239], v172 offset:5120
	ds_read_b128 v[240:243], v172 offset:6144
	ds_read_b128 v[244:247], v172 offset:7168
	global_load_lds_dwordx4 v136, s[14:15]
	s_add_i32 m0, s3, 0xe000
	s_nop 0
	global_load_lds_dwordx4 v138, s[14:15]
	s_waitcnt vmcnt(8)
	s_waitcnt lgkmcnt(0)
	s_barrier
	s_setprio 1
	s_waitcnt lgkmcnt(0)
	v_mfma_f32_16x16x32_bf16 v[126:129], v[174:177], v[216:219], v[126:129]
	v_mfma_f32_16x16x32_bf16 v[122:125], v[182:185], v[216:219], v[122:125]
	v_mfma_f32_16x16x32_bf16 v[118:121], v[174:177], v[224:227], v[118:121]
	v_mfma_f32_16x16x32_bf16 v[114:117], v[182:185], v[224:227], v[114:117]
	v_mfma_f32_16x16x32_bf16 v[102:105], v[174:177], v[232:235], v[102:105]
	v_mfma_f32_16x16x32_bf16 v[98:101], v[182:185], v[232:235], v[98:101]
	v_mfma_f32_16x16x32_bf16 v[86:89], v[174:177], v[240:243], v[86:89]
	v_mfma_f32_16x16x32_bf16 v[82:85], v[182:185], v[240:243], v[82:85]
	v_mfma_f32_16x16x32_bf16 v[126:129], v[178:181], v[220:223], v[126:129]
	v_mfma_f32_16x16x32_bf16 v[122:125], v[186:189], v[220:223], v[122:125]
	v_mfma_f32_16x16x32_bf16 v[118:121], v[178:181], v[228:231], v[118:121]
	v_mfma_f32_16x16x32_bf16 v[114:117], v[186:189], v[228:231], v[114:117]
	v_mfma_f32_16x16x32_bf16 v[102:105], v[178:181], v[236:239], v[102:105]
	v_mfma_f32_16x16x32_bf16 v[98:101], v[186:189], v[236:239], v[98:101]
	v_mfma_f32_16x16x32_bf16 v[86:89], v[178:181], v[244:247], v[86:89]
	v_mfma_f32_16x16x32_bf16 v[82:85], v[186:189], v[244:247], v[82:85]
	s_setprio 0
	s_setprio 1
	v_mfma_f32_16x16x32_bf16 v[110:113], v[190:193], v[216:219], v[110:113]
	v_mfma_f32_16x16x32_bf16 v[106:109], v[198:201], v[216:219], v[106:109]
	v_mfma_f32_16x16x32_bf16 v[94:97], v[190:193], v[224:227], v[94:97]
	v_mfma_f32_16x16x32_bf16 v[90:93], v[198:201], v[224:227], v[90:93]
	v_mfma_f32_16x16x32_bf16 v[78:81], v[190:193], v[232:235], v[78:81]
	v_mfma_f32_16x16x32_bf16 v[74:77], v[198:201], v[232:235], v[74:77]
	v_mfma_f32_16x16x32_bf16 v[70:73], v[190:193], v[240:243], v[70:73]
	v_mfma_f32_16x16x32_bf16 v[66:69], v[198:201], v[240:243], v[66:69]
	v_mfma_f32_16x16x32_bf16 v[110:113], v[194:197], v[220:223], v[110:113]
	v_mfma_f32_16x16x32_bf16 v[106:109], v[202:205], v[220:223], v[106:109]
	v_mfma_f32_16x16x32_bf16 v[94:97], v[194:197], v[228:231], v[94:97]
	v_mfma_f32_16x16x32_bf16 v[90:93], v[202:205], v[228:231], v[90:93]
	v_mfma_f32_16x16x32_bf16 v[78:81], v[194:197], v[236:239], v[78:81]
	v_mfma_f32_16x16x32_bf16 v[74:77], v[202:205], v[236:239], v[74:77]
	v_mfma_f32_16x16x32_bf16 v[70:73], v[194:197], v[244:247], v[70:73]
	v_mfma_f32_16x16x32_bf16 v[66:69], v[202:205], v[244:247], v[66:69]
	s_setprio 0
	s_barrier
	s_add_i32 s43, s43, s26
	s_mov_b32 m0, s43
	ds_read_b128 v[216:219], v172 offset:16384
	ds_read_b128 v[220:223], v172 offset:17408
	ds_read_b128 v[224:227], v172 offset:18432
	ds_read_b128 v[228:231], v172 offset:19456
	ds_read_b128 v[232:235], v172 offset:20480
	ds_read_b128 v[236:239], v172 offset:21504
	ds_read_b128 v[240:243], v172 offset:22528
	ds_read_b128 v[244:247], v172 offset:23552
	global_load_lds_dwordx4 v0, s[16:17]
	s_add_i32 m0, s43, 0x2000
	s_add_u32 s44, s16, 0x80000
	s_addc_u32 s45, s17, 0
	s_add_i32 s43, s46, s26
	global_load_lds_dwordx4 v134, s[16:17]
	s_mov_b32 m0, s43
	s_nop 0
	global_load_lds_dwordx4 v0, s[44:45]
	s_add_i32 m0, s43, 0x2000
	s_nop 0
	global_load_lds_dwordx4 v134, s[44:45]
	s_mov_b32 m0, s3
	s_nop 0
	global_load_lds_dwordx4 v130, s[18:19]
	s_mov_b32 m0, s27
	s_nop 0
	global_load_lds_dwordx4 v132, s[18:19]
	s_waitcnt vmcnt(8)
	s_waitcnt lgkmcnt(0)
	s_barrier
	s_setprio 1
	s_waitcnt lgkmcnt(0)
	v_mfma_f32_16x16x32_bf16 v[62:65], v[174:177], v[216:219], v[62:65]
	v_mfma_f32_16x16x32_bf16 v[58:61], v[182:185], v[216:219], v[58:61]
	v_mfma_f32_16x16x32_bf16 v[54:57], v[174:177], v[224:227], v[54:57]
	v_mfma_f32_16x16x32_bf16 v[50:53], v[182:185], v[224:227], v[50:53]
	v_mfma_f32_16x16x32_bf16 v[38:41], v[174:177], v[232:235], v[38:41]
	v_mfma_f32_16x16x32_bf16 v[34:37], v[182:185], v[232:235], v[34:37]
	v_mfma_f32_16x16x32_bf16 v[22:25], v[174:177], v[240:243], v[22:25]
	v_mfma_f32_16x16x32_bf16 v[18:21], v[182:185], v[240:243], v[18:21]
	v_mfma_f32_16x16x32_bf16 v[62:65], v[178:181], v[220:223], v[62:65]
	v_mfma_f32_16x16x32_bf16 v[58:61], v[186:189], v[220:223], v[58:61]
	v_mfma_f32_16x16x32_bf16 v[54:57], v[178:181], v[228:231], v[54:57]
	v_mfma_f32_16x16x32_bf16 v[50:53], v[186:189], v[228:231], v[50:53]
	v_mfma_f32_16x16x32_bf16 v[38:41], v[178:181], v[236:239], v[38:41]
	v_mfma_f32_16x16x32_bf16 v[34:37], v[186:189], v[236:239], v[34:37]
	v_mfma_f32_16x16x32_bf16 v[22:25], v[178:181], v[244:247], v[22:25]
	v_mfma_f32_16x16x32_bf16 v[18:21], v[186:189], v[244:247], v[18:21]
	s_setprio 0
	s_setprio 1
	v_mfma_f32_16x16x32_bf16 v[46:49], v[190:193], v[216:219], v[46:49]
	v_mfma_f32_16x16x32_bf16 v[42:45], v[198:201], v[216:219], v[42:45]
	v_mfma_f32_16x16x32_bf16 v[30:33], v[190:193], v[224:227], v[30:33]
	v_mfma_f32_16x16x32_bf16 v[26:29], v[198:201], v[224:227], v[26:29]
	v_mfma_f32_16x16x32_bf16 v[14:17], v[190:193], v[232:235], v[14:17]
	v_mfma_f32_16x16x32_bf16 v[10:13], v[198:201], v[232:235], v[10:13]
	v_mfma_f32_16x16x32_bf16 v[6:9], v[190:193], v[240:243], v[6:9]
	v_mfma_f32_16x16x32_bf16 v[2:5], v[198:201], v[240:243], v[2:5]
	v_mfma_f32_16x16x32_bf16 v[46:49], v[194:197], v[220:223], v[46:49]
	v_mfma_f32_16x16x32_bf16 v[42:45], v[202:205], v[220:223], v[42:45]
	v_mfma_f32_16x16x32_bf16 v[30:33], v[194:197], v[228:231], v[30:33]
	v_mfma_f32_16x16x32_bf16 v[26:29], v[202:205], v[228:231], v[26:29]
	v_mfma_f32_16x16x32_bf16 v[14:17], v[194:197], v[236:239], v[14:17]
	v_mfma_f32_16x16x32_bf16 v[10:13], v[202:205], v[236:239], v[10:13]
	v_mfma_f32_16x16x32_bf16 v[6:9], v[194:197], v[244:247], v[6:9]
	v_mfma_f32_16x16x32_bf16 v[2:5], v[202:205], v[244:247], v[2:5]
	s_setprio 0
	s_barrier
; #define PG8_STAGE(bufoff, gbase, voff) do { _Pragma("unroll") for (int _i = 0; _i < 2; ++_i) \
;         __builtin_amdgcn_global_load_lds((const unsigned*)((const char*)(gbase) + (voff)[_i]), (PG8_LAS unsigned*)(lds + (bufoff) + ldsw + _i * 8192), 16, 0, 0); } while (0)
; #define PG8_LDA(dst, b, h) do { _Pragma("unroll") for (int m = 0; m < 4; ++m) _Pragma("unroll") for (int k = 0; k < 2; ++k) dst[m][k] = *(const PG8_LAS bf16x8*)(lds + PG8_SA(b, h) + aoff + m * 2048 + k * 1024); } while (0)
; #define PG8_LDB(dst, b, h) do { _Pragma("unroll") for (int n = 0; n < 2; ++n) _Pragma("unroll") for (int k = 0; k < 2; ++k) dst[n][k] = *(const PG8_LAS bf16x8*)(lds + PG8_SB(b, h) + boff + n * 2048 + k * 1024); } while (0)
; #define PG8_MMA(ai, bj, At, Bt) do { __builtin_amdgcn_s_setprio(1); _Pragma("unroll") for (int m = 0; m < 4; ++m) _Pragma("unroll") for (int n = 0; n < 2; ++n) _Pragma("unroll") for (int k = 0; k < 2; ++k) \
;         acc[ai][bj][m][n] = __builtin_amdgcn_mfma_f32_16x16x32_bf16(Bt[n][k], At[m][k], acc[ai][bj][m][n], 0, 0, 0); __builtin_amdgcn_s_setprio(0); } while (0)
; #define PG8_WAIT_V(n) asm volatile("s_waitcnt vmcnt(" #n ")" ::: "memory")
; #define PG8_WAIT_L(n) asm volatile("s_waitcnt lgkmcnt(" #n ")" ::: "memory")
; #define PG8_BAR __builtin_amdgcn_s_barrier()
; #define PG8_SCHED __builtin_amdgcn_sched_barrier(0)
; template <class Epi, class Sched, bool ALIGN_EPI = false, bool SP2 = false>
; __device__ __forceinline__ void gemm_phase(PG8_LAS unsigned char* lds, const Gemm g, const Sched& S, const Epi& E, const int tid) {
;     ...
;             PG8_LDB(B0, 1, 0); PG8_LDB(B1, 1, 1); PG8_SCHED; PG8_LDA(At, 1, 0); PG8_STAGE(PG8_SA(0, 1), a2 + hstep, voffA);
;             PG8_WAIT_V(8); PG8_WAIT_L(0); PG8_BAR; PG8_MMA(0, 0, At, B0); PG8_MMA(0, 1, At, B1); PG8_BAR; PG8_SCHED;
;             PG8_LDA(At, 1, 1); PG8_STAGE(PG8_SB(1, 0), b3, voffB); PG8_STAGE(PG8_SB(1, 1), b3 + hstep, voffB); PG8_STAGE(PG8_SA(1, 0), a3, voffA);
;             PG8_WAIT_V(8); PG8_WAIT_L(0); PG8_BAR; PG8_MMA(1, 0, At, B0); PG8_MMA(1, 1, At, B1); PG8_BAR; PG8_SCHED;
	s_add_i32 s43, 0, 0x18000
	v_add_u32_e32 v173, s43, v170
	s_add_i32 s44, 0, 0x1c000
	ds_read_b128 v[174:177], v173
	ds_read_b128 v[178:181], v173 offset:1024
	ds_read_b128 v[182:185], v173 offset:2048
	ds_read_b128 v[186:189], v173 offset:3072
	v_add_u32_e32 v173, s44, v170
	ds_read_b128 v[190:193], v173
	ds_read_b128 v[194:197], v173 offset:1024
	ds_read_b128 v[198:201], v173 offset:2048
	ds_read_b128 v[202:205], v173 offset:3072
	s_add_u32 s18, s18, 0x80000
	s_addc_u32 s19, s19, 0
	s_mov_b32 m0, s28
	ds_read_b128 v[216:219], v172 offset:32768
	ds_read_b128 v[220:223], v172 offset:33792
	ds_read_b128 v[224:227], v172 offset:34816
	ds_read_b128 v[228:231], v172 offset:35840
	ds_read_b128 v[232:235], v172 offset:36864
	ds_read_b128 v[236:239], v172 offset:37888
	ds_read_b128 v[240:243], v172 offset:38912
	ds_read_b128 v[244:247], v172 offset:39936
	global_load_lds_dwordx4 v130, s[18:19]
	s_mov_b32 m0, s30
	s_nop 0
	global_load_lds_dwordx4 v132, s[18:19]
	s_waitcnt vmcnt(8)
	s_waitcnt lgkmcnt(0)
	s_barrier
	s_setprio 1
	s_waitcnt lgkmcnt(0)
	v_mfma_f32_16x16x32_bf16 v[126:129], v[174:177], v[216:219], v[126:129]
	v_mfma_f32_16x16x32_bf16 v[122:125], v[182:185], v[216:219], v[122:125]
	v_mfma_f32_16x16x32_bf16 v[118:121], v[174:177], v[224:227], v[118:121]
	v_mfma_f32_16x16x32_bf16 v[114:117], v[182:185], v[224:227], v[114:117]
	v_mfma_f32_16x16x32_bf16 v[102:105], v[174:177], v[232:235], v[102:105]
	v_mfma_f32_16x16x32_bf16 v[98:101], v[182:185], v[232:235], v[98:101]
	v_mfma_f32_16x16x32_bf16 v[86:89], v[174:177], v[240:243], v[86:89]
	v_mfma_f32_16x16x32_bf16 v[82:85], v[182:185], v[240:243], v[82:85]
	v_mfma_f32_16x16x32_bf16 v[126:129], v[178:181], v[220:223], v[126:129]
	v_mfma_f32_16x16x32_bf16 v[122:125], v[186:189], v[220:223], v[122:125]
	v_mfma_f32_16x16x32_bf16 v[118:121], v[178:181], v[228:231], v[118:121]
	v_mfma_f32_16x16x32_bf16 v[114:117], v[186:189], v[228:231], v[114:117]
	v_mfma_f32_16x16x32_bf16 v[102:105], v[178:181], v[236:239], v[102:105]
	v_mfma_f32_16x16x32_bf16 v[98:101], v[186:189], v[236:239], v[98:101]
	v_mfma_f32_16x16x32_bf16 v[86:89], v[178:181], v[244:247], v[86:89]
	v_mfma_f32_16x16x32_bf16 v[82:85], v[186:189], v[244:247], v[82:85]
	s_setprio 0
	s_setprio 1
	v_mfma_f32_16x16x32_bf16 v[110:113], v[190:193], v[216:219], v[110:113]
	v_mfma_f32_16x16x32_bf16 v[106:109], v[198:201], v[216:219], v[106:109]
	v_mfma_f32_16x16x32_bf16 v[94:97], v[190:193], v[224:227], v[94:97]
	v_mfma_f32_16x16x32_bf16 v[90:93], v[198:201], v[224:227], v[90:93]
	v_mfma_f32_16x16x32_bf16 v[78:81], v[190:193], v[232:235], v[78:81]
	v_mfma_f32_16x16x32_bf16 v[74:77], v[198:201], v[232:235], v[74:77]
	v_mfma_f32_16x16x32_bf16 v[70:73], v[190:193], v[240:243], v[70:73]
	v_mfma_f32_16x16x32_bf16 v[66:69], v[198:201], v[240:243], v[66:69]
	v_mfma_f32_16x16x32_bf16 v[110:113], v[194:197], v[220:223], v[110:113]
	v_mfma_f32_16x16x32_bf16 v[106:109], v[202:205], v[220:223], v[106:109]
	v_mfma_f32_16x16x32_bf16 v[94:97], v[194:197], v[228:231], v[94:97]
	v_mfma_f32_16x16x32_bf16 v[90:93], v[202:205], v[228:231], v[90:93]
	v_mfma_f32_16x16x32_bf16 v[78:81], v[194:197], v[236:239], v[78:81]
	v_mfma_f32_16x16x32_bf16 v[74:77], v[202:205], v[236:239], v[74:77]
	v_mfma_f32_16x16x32_bf16 v[70:73], v[194:197], v[244:247], v[70:73]
	v_mfma_f32_16x16x32_bf16 v[66:69], v[202:205], v[244:247], v[66:69]
	s_setprio 0
	s_barrier
	s_add_i32 m0, s43, s26
	s_add_u32 s16, s16, 0x80
	s_addc_u32 s17, s17, 0
	ds_read_b128 v[216:219], v172 offset:49152
	ds_read_b128 v[220:223], v172 offset:50176
	ds_read_b128 v[224:227], v172 offset:51200
	ds_read_b128 v[228:231], v172 offset:52224
	ds_read_b128 v[232:235], v172 offset:53248
	ds_read_b128 v[236:239], v172 offset:54272
	ds_read_b128 v[240:243], v172 offset:55296
	ds_read_b128 v[244:247], v172 offset:56320
	global_load_lds_dwordx4 v0, s[16:17]
	s_add_i32 m0, m0, 0x2000
	s_nop 0
	global_load_lds_dwordx4 v134, s[16:17]
	s_nop 0
	s_add_u32 s16, s16, 0x80000
	s_addc_u32 s17, s17, 0
	s_add_i32 m0, s44, s26
	s_nop 0
	global_load_lds_dwordx4 v0, s[16:17]
	s_add_i32 m0, m0, 0x2000
	s_nop 0
	global_load_lds_dwordx4 v134, s[16:17]
	s_add_u32 s18, s18, 0xfff80080
	s_addc_u32 s19, s19, -1
	s_mov_b32 m0, s31
	s_nop 0
	global_load_lds_dwordx4 v130, s[18:19]
	s_mov_b32 m0, s34
	s_nop 0
	global_load_lds_dwordx4 v132, s[18:19]
	s_waitcnt vmcnt(8)
	s_waitcnt lgkmcnt(0)
	s_barrier
	s_setprio 1
	s_waitcnt lgkmcnt(0)
	v_mfma_f32_16x16x32_bf16 v[62:65], v[174:177], v[216:219], v[62:65]
	v_mfma_f32_16x16x32_bf16 v[58:61], v[182:185], v[216:219], v[58:61]
	v_mfma_f32_16x16x32_bf16 v[54:57], v[174:177], v[224:227], v[54:57]
	v_mfma_f32_16x16x32_bf16 v[50:53], v[182:185], v[224:227], v[50:53]
	v_mfma_f32_16x16x32_bf16 v[38:41], v[174:177], v[232:235], v[38:41]
	v_mfma_f32_16x16x32_bf16 v[34:37], v[182:185], v[232:235], v[34:37]
	v_mfma_f32_16x16x32_bf16 v[22:25], v[174:177], v[240:243], v[22:25]
	v_mfma_f32_16x16x32_bf16 v[18:21], v[182:185], v[240:243], v[18:21]
	v_mfma_f32_16x16x32_bf16 v[62:65], v[178:181], v[220:223], v[62:65]
	v_mfma_f32_16x16x32_bf16 v[58:61], v[186:189], v[220:223], v[58:61]
	v_mfma_f32_16x16x32_bf16 v[54:57], v[178:181], v[228:231], v[54:57]
	v_mfma_f32_16x16x32_bf16 v[50:53], v[186:189], v[228:231], v[50:53]
	v_mfma_f32_16x16x32_bf16 v[38:41], v[178:181], v[236:239], v[38:41]
	v_mfma_f32_16x16x32_bf16 v[34:37], v[186:189], v[236:239], v[34:37]
	v_mfma_f32_16x16x32_bf16 v[22:25], v[178:181], v[244:247], v[22:25]
	v_mfma_f32_16x16x32_bf16 v[18:21], v[186:189], v[244:247], v[18:21]
	s_setprio 0
	s_setprio 1
	v_mfma_f32_16x16x32_bf16 v[46:49], v[190:193], v[216:219], v[46:49]
	v_mfma_f32_16x16x32_bf16 v[42:45], v[198:201], v[216:219], v[42:45]
	v_mfma_f32_16x16x32_bf16 v[30:33], v[190:193], v[224:227], v[30:33]
	v_mfma_f32_16x16x32_bf16 v[26:29], v[198:201], v[224:227], v[26:29]
	v_mfma_f32_16x16x32_bf16 v[14:17], v[190:193], v[232:235], v[14:17]
	v_mfma_f32_16x16x32_bf16 v[10:13], v[198:201], v[232:235], v[10:13]
	v_mfma_f32_16x16x32_bf16 v[6:9], v[190:193], v[240:243], v[6:9]
	v_mfma_f32_16x16x32_bf16 v[2:5], v[198:201], v[240:243], v[2:5]
	v_mfma_f32_16x16x32_bf16 v[46:49], v[194:197], v[220:223], v[46:49]
	v_mfma_f32_16x16x32_bf16 v[42:45], v[202:205], v[220:223], v[42:45]
	v_mfma_f32_16x16x32_bf16 v[30:33], v[194:197], v[228:231], v[30:33]
	v_mfma_f32_16x16x32_bf16 v[26:29], v[202:205], v[228:231], v[26:29]
	v_mfma_f32_16x16x32_bf16 v[14:17], v[194:197], v[236:239], v[14:17]
	v_mfma_f32_16x16x32_bf16 v[10:13], v[202:205], v[236:239], v[10:13]
	v_mfma_f32_16x16x32_bf16 v[6:9], v[194:197], v[244:247], v[6:9]
	v_mfma_f32_16x16x32_bf16 v[2:5], v[202:205], v[244:247], v[2:5]
	s_setprio 0
	s_barrier
; __device__ __forceinline__ unsigned pk2(float lo, float hi) { f32x2 v = {lo, hi}; hbf2 b = __builtin_convertvector(v, hbf2); return __builtin_bit_cast(unsigned, b); }
;     __device__ __forceinline__ void operator()(const f32x4 (&acc)[2][2][4][2], const Unit& u, int wr, int wc, int fr, int fq) const {
;         const int row0 = u.pm * BM + wr * 64 + fr, col0 = u.pn * BM + wc * 32 + 8 * fq;
; #pragma unroll
;         for (int ai = 0; ai < 2; ++ai)
; #pragma unroll
;             for (int m = 0; m < 4; ++m) { bf16_t* rowp = O + (size_t)(row0 + ai * HALF + m * 16) * ldc + col0;
; #pragma unroll
;                 for (int bj = 0; bj < 2; ++bj) { const f32x4 v0 = acc[ai][bj][m][0], v1 = acc[ai][bj][m][1];
;                     u32x4 w; w.x = pk2(v0[0], v0[1]); w.y = pk2(v0[2], v0[3]); w.z = pk2(v1[0], v1[1]); w.w = pk2(v1[2], v1[3]);
;                     if constexpr (NT) __builtin_nontemporal_store(w, (u32x4*)(rowp + bj * HALF)); else *(u32x4*)(rowp + bj * HALF) = w; } }
	s_add_i32 s42, s42, 2
	s_add_u32 s14, s14, 0x100
	s_addc_u32 s15, s15, 0
	s_add_u32 s40, s40, 0x100
	s_addc_u32 s41, s41, 0
	s_cmp_gt_u32 s42, 29
	s_cbranch_scc0 .LBB0_496
	v_lshl_add_u32 v152, s2, 8, v169
	v_lshl_or_b32 v174, s37, 8, v171
	v_ashrrev_i32_e32 v153, 31, v152
	v_ashrrev_i32_e32 v175, 31, v174
	v_lshlrev_b64 v[176:177], 12, v[152:153]
	v_lshl_add_u64 v[176:177], s[84:85], 0, v[176:177]
	v_lshlrev_b64 v[174:175], 1, v[174:175]
	v_lshl_add_u64 v[176:177], v[176:177], 0, v[174:175]
	s_mov_b32 s2, 0x80000
	s_mov_b64 s[14:15], 0x80000
	v_cvt_pk_bf16_f32 v62, v62, v63
	v_cvt_pk_bf16_f32 v63, v64, v65
	v_cvt_pk_bf16_f32 v64, v58, v59
	v_add_co_u32_e32 v58, vcc, s2, v176
	v_cvt_pk_bf16_f32 v70, v70, v71
	v_cvt_pk_bf16_f32 v71, v72, v73
	v_cvt_pk_bf16_f32 v72, v66, v67
	v_lshl_add_u64 v[66:67], v[176:177], 0, s[14:15]
	v_addc_co_u32_e32 v59, vcc, 0, v177, vcc
	v_cvt_pk_bf16_f32 v46, v46, v47
	v_cvt_pk_bf16_f32 v47, v48, v49
	v_cvt_pk_bf16_f32 v48, v42, v43
	v_cvt_pk_bf16_f32 v49, v44, v45
	s_mov_b32 s2, 0x90000
	v_cvt_pk_bf16_f32 v110, v110, v111
	v_cvt_pk_bf16_f32 v111, v112, v113
	v_cvt_pk_bf16_f32 v112, v106, v107
	v_or_b32_e32 v106, 16, v152
	global_store_dwordx4 v[66:67], v[46:49], off offset:256
	s_mov_b64 s[14:15], 0x90000
	v_ashrrev_i32_e32 v107, 31, v106
	v_add_co_u32_e32 v48, vcc, s2, v176
	v_cvt_pk_bf16_f32 v94, v94, v95
	v_cvt_pk_bf16_f32 v95, v96, v97
	v_cvt_pk_bf16_f32 v96, v90, v91
	v_or_b32_e32 v90, 32, v152
	v_lshl_add_u64 v[46:47], v[176:177], 0, s[14:15]
	v_addc_co_u32_e32 v49, vcc, 0, v177, vcc
	v_cvt_pk_bf16_f32 v30, v30, v31
	v_cvt_pk_bf16_f32 v31, v32, v33
	v_cvt_pk_bf16_f32 v32, v26, v27
	v_cvt_pk_bf16_f32 v33, v28, v29
	s_mov_b32 s2, 0xa0000
	v_lshlrev_b64 v[106:107], 12, v[106:107]
	v_ashrrev_i32_e32 v91, 31, v90
	v_cvt_pk_bf16_f32 v78, v78, v79
	v_cvt_pk_bf16_f32 v79, v80, v81
	v_cvt_pk_bf16_f32 v80, v74, v75
	v_or_b32_e32 v74, 48, v152
	global_store_dwordx4 v[46:47], v[30:33], off offset:256
	s_mov_b64 s[14:15], 0xa0000
	v_cvt_pk_bf16_f32 v113, v108, v109
	v_add_co_u32_e32 v32, vcc, s2, v176
	v_lshl_add_u64 v[106:107], s[84:85], 0, v[106:107]
	v_lshlrev_b64 v[90:91], 12, v[90:91]
	v_ashrrev_i32_e32 v75, 31, v74
	v_lshl_add_u64 v[30:31], v[176:177], 0, s[14:15]
	v_addc_co_u32_e32 v33, vcc, 0, v177, vcc
	v_cvt_pk_bf16_f32 v14, v14, v15
	v_cvt_pk_bf16_f32 v15, v16, v17
	v_cvt_pk_bf16_f32 v16, v10, v11
	v_cvt_pk_bf16_f32 v17, v12, v13
	s_mov_b32 s2, 0xb0000
	global_store_dwordx4 v[176:177], v[110:113], off offset:256
	v_cvt_pk_bf16_f32 v97, v92, v93
	v_lshl_add_u64 v[90:91], s[84:85], 0, v[90:91]
	v_lshl_add_u64 v[110:111], v[106:107], 0, v[174:175]
	v_lshlrev_b64 v[74:75], 12, v[74:75]
	global_store_dwordx4 v[30:31], v[14:17], off offset:256
	global_store_dwordx4 v[110:111], v[94:97], off offset:256
	v_cvt_pk_bf16_f32 v81, v76, v77
	v_add_co_u32_e32 v16, vcc, s2, v176
	v_lshl_add_u64 v[94:95], v[90:91], 0, v[174:175]
	v_lshl_add_u64 v[74:75], s[84:85], 0, v[74:75]
	s_mov_b64 s[14:15], 0xb0000
	v_addc_co_u32_e32 v17, vcc, 0, v177, vcc
	v_cvt_pk_bf16_f32 v126, v126, v127
	v_cvt_pk_bf16_f32 v127, v128, v129
	v_cvt_pk_bf16_f32 v128, v122, v123
	v_cvt_pk_bf16_f32 v129, v124, v125
	v_cvt_pk_bf16_f32 v106, v118, v119
	v_cvt_pk_bf16_f32 v107, v120, v121
	v_cvt_pk_bf16_f32 v108, v114, v115
	v_cvt_pk_bf16_f32 v109, v116, v117
	v_cvt_pk_bf16_f32 v90, v102, v103
	v_cvt_pk_bf16_f32 v91, v104, v105
	v_cvt_pk_bf16_f32 v92, v98, v99
	v_cvt_pk_bf16_f32 v93, v100, v101
	global_store_dwordx4 v[94:95], v[78:81], off offset:256
	v_cvt_pk_bf16_f32 v76, v82, v83
	v_cvt_pk_bf16_f32 v77, v84, v85
	v_lshl_add_u64 v[78:79], v[74:75], 0, v[174:175]
	v_cvt_pk_bf16_f32 v74, v86, v87
	v_cvt_pk_bf16_f32 v75, v88, v89
	v_cvt_pk_bf16_f32 v73, v68, v69
	v_cvt_pk_bf16_f32 v65, v60, v61
	v_cvt_pk_bf16_f32 v42, v54, v55
	v_cvt_pk_bf16_f32 v43, v56, v57
	v_cvt_pk_bf16_f32 v44, v50, v51
	v_cvt_pk_bf16_f32 v45, v52, v53
	v_cvt_pk_bf16_f32 v26, v38, v39
	v_cvt_pk_bf16_f32 v27, v40, v41
	v_cvt_pk_bf16_f32 v28, v34, v35
	v_cvt_pk_bf16_f32 v29, v36, v37
	v_lshl_add_u64 v[14:15], v[176:177], 0, s[14:15]
	v_cvt_pk_bf16_f32 v10, v22, v23
	v_cvt_pk_bf16_f32 v11, v24, v25
	v_cvt_pk_bf16_f32 v12, v18, v19
	v_cvt_pk_bf16_f32 v13, v20, v21
	v_cvt_pk_bf16_f32 v6, v6, v7
	v_cvt_pk_bf16_f32 v7, v8, v9
	v_cvt_pk_bf16_f32 v8, v2, v3
	v_cvt_pk_bf16_f32 v9, v4, v5
	s_and_b64 vcc, exec, s[4:5]
	s_mov_b32 s37, s6
	s_mov_b32 s2, s8
	s_mov_b64 s[16:17], s[12:13]
	s_mov_b64 s[14:15], s[10:11]
	global_store_dwordx4 v[176:177], v[126:129], off
	global_store_dwordx4 v[110:111], v[106:109], off
	global_store_dwordx4 v[94:95], v[90:93], off
	global_store_dwordx4 v[78:79], v[74:77], off
	global_store_dwordx4 v[78:79], v[70:73], off offset:256
	global_store_dwordx4 v[58:59], v[62:65], off
	global_store_dwordx4 v[48:49], v[42:45], off
	global_store_dwordx4 v[32:33], v[26:29], off
	global_store_dwordx4 v[16:17], v[10:13], off
	global_store_dwordx4 v[14:15], v[6:9], off offset:256
	s_cbranch_vccz .LBB0_489
	s_waitcnt vmcnt(0)
	s_cmpk_gt_u32 s24, 0xff
	s_cbranch_scc1 .LBB0_500
	s_barrier
